# v6: second epilogue half interleaved between MFMAs of the peeled iteration; output stores marked nt
# speedup vs baseline: 1.0186x; 1.0029x over previous
.Lmy_b16_pdefer:
	s_add_u32 s1, s12, 0xfffc0080
	s_addc_u32 s14, s13, -1
	s_add_i32 s33, 0, 0x10000
	s_cmp_eq_u32 s73, 12
	s_cselect_b32 s29, s11, s14
	s_cselect_b32 s28, s30, s1
	v_add_u32_e32 v100, s33, v154
	s_cselect_b32 s15, s31, s55
	s_cselect_b32 s14, s47, s54
	s_add_i32 s1, 0, 0x14000
	ds_read_b128 v[144:147], v100
	ds_read_b128 v[148:151], v100 offset:1024
	ds_read_b128 v[158:161], v100 offset:2048
	ds_read_b128 v[162:165], v100 offset:3072
	v_add_u32_e32 v100, s1, v154
	ds_read_b128 v[166:169], v100
	ds_read_b128 v[170:173], v100 offset:1024
	ds_read_b128 v[174:177], v100 offset:2048
	ds_read_b128 v[178:181], v100 offset:3072
	v_lshl_add_u64 v[152:153], s[12:13], 0, v[140:141]
	s_add_i32 m0, s41, 0xc000
	ds_read_b128 v[182:185], v156
	ds_read_b128 v[186:189], v156 offset:1024
	ds_read_b128 v[190:193], v156 offset:2048
	ds_read_b128 v[194:197], v156 offset:3072
	ds_read_b128 v[198:201], v156 offset:4096
	ds_read_b128 v[202:205], v156 offset:5120
	ds_read_b128 v[208:211], v156 offset:6144
	ds_read_b128 v[226:229], v156 offset:7168
	global_load_lds_dwordx4 v[152:153], off
	v_lshl_add_u64 v[152:153], s[12:13], 0, v[142:143]
	s_add_i32 m0, s41, 0xe000
	s_nop 0
	global_load_lds_dwordx4 v[152:153], off
	v_and_b32_e32 v100, 3, v224
	v_lshlrev_b32_e32 v100, 6, v100
	v_and_or_b32 v100, v224, 60, v100
	v_mov_b32_e32 v152, v247
	v_add_u32_e32 v153, s32, v247
	v_fmamk_f32 v234, v236, 0x3a800000, v207
	v_rsq_f32_e32 v234, v234
	s_nop 0
	v_mul_f32_e32 v234, s36, v234
	v_pk_mul_f32 v[126:127], v[126:127], v[234:235] op_sel_hi:[1,0]
	v_pk_mul_f32 v[128:129], v[128:129], v[234:235] op_sel_hi:[1,0]
	v_pk_mul_f32 v[122:123], v[122:123], v[234:235] op_sel_hi:[1,0]
	v_pk_mul_f32 v[124:125], v[124:125], v[234:235] op_sel_hi:[1,0]
	v_cvt_pk_bf16_f32 v126, v126, v127
	v_cvt_pk_bf16_f32 v127, v128, v129
	v_cvt_pk_bf16_f32 v128, v122, v123
	v_cvt_pk_bf16_f32 v129, v124, v125
	ds_bpermute_b32 v122, v100, v126
	ds_bpermute_b32 v123, v100, v127
	ds_bpermute_b32 v124, v100, v128
	ds_bpermute_b32 v125, v100, v129
	v_pk_mul_f32 v[118:119], v[118:119], v[234:235] op_sel_hi:[1,0]
	v_pk_mul_f32 v[120:121], v[120:121], v[234:235] op_sel_hi:[1,0]
	v_pk_mul_f32 v[114:115], v[114:115], v[234:235] op_sel_hi:[1,0]
	v_pk_mul_f32 v[116:117], v[116:117], v[234:235] op_sel_hi:[1,0]
	v_cvt_pk_bf16_f32 v118, v118, v119
	v_cvt_pk_bf16_f32 v119, v120, v121
	v_cvt_pk_bf16_f32 v120, v114, v115
	v_cvt_pk_bf16_f32 v121, v116, v117
	ds_bpermute_b32 v114, v100, v118
	ds_bpermute_b32 v115, v100, v119
	ds_bpermute_b32 v116, v100, v120
	ds_bpermute_b32 v117, v100, v121
	s_waitcnt lgkmcnt(4)
	global_store_dwordx4 v152, v[122:125], s[2:3] nt
	v_add_u32_e32 v152, s0, v152
	v_fmamk_f32 v234, v237, 0x3a800000, v207
	v_rsq_f32_e32 v234, v234
	s_nop 0
	v_mul_f32_e32 v234, s36, v234
	v_pk_mul_f32 v[110:111], v[110:111], v[234:235] op_sel_hi:[1,0]
	v_pk_mul_f32 v[112:113], v[112:113], v[234:235] op_sel_hi:[1,0]
	v_pk_mul_f32 v[106:107], v[106:107], v[234:235] op_sel_hi:[1,0]
	v_pk_mul_f32 v[108:109], v[108:109], v[234:235] op_sel_hi:[1,0]
	v_cvt_pk_bf16_f32 v110, v110, v111
	v_cvt_pk_bf16_f32 v111, v112, v113
	v_cvt_pk_bf16_f32 v112, v106, v107
	v_cvt_pk_bf16_f32 v113, v108, v109
	ds_bpermute_b32 v106, v100, v110
	ds_bpermute_b32 v107, v100, v111
	ds_bpermute_b32 v108, v100, v112
	ds_bpermute_b32 v109, v100, v113
	s_waitcnt lgkmcnt(4)
	global_store_dwordx4 v153, v[114:117], s[2:3] nt
	v_add_u32_e32 v153, s0, v153
	v_pk_mul_f32 v[102:103], v[102:103], v[234:235] op_sel_hi:[1,0]
	v_pk_mul_f32 v[104:105], v[104:105], v[234:235] op_sel_hi:[1,0]
	v_pk_mul_f32 v[96:97], v[96:97], v[234:235] op_sel_hi:[1,0]
	v_pk_mul_f32 v[98:99], v[98:99], v[234:235] op_sel_hi:[1,0]
	v_cvt_pk_bf16_f32 v102, v102, v103
	v_cvt_pk_bf16_f32 v103, v104, v105
	v_cvt_pk_bf16_f32 v104, v96, v97
	v_cvt_pk_bf16_f32 v105, v98, v99
	ds_bpermute_b32 v96, v100, v102
	ds_bpermute_b32 v97, v100, v103
	ds_bpermute_b32 v98, v100, v104
	ds_bpermute_b32 v99, v100, v105
	s_waitcnt lgkmcnt(4)
	global_store_dwordx4 v152, v[106:109], s[2:3] nt
	v_add_u32_e32 v152, s0, v152
	v_fmamk_f32 v234, v238, 0x3a800000, v207
	v_rsq_f32_e32 v234, v234
	s_nop 0
	v_mul_f32_e32 v234, s36, v234
	v_pk_mul_f32 v[92:93], v[92:93], v[234:235] op_sel_hi:[1,0]
	v_pk_mul_f32 v[94:95], v[94:95], v[234:235] op_sel_hi:[1,0]
	v_pk_mul_f32 v[88:89], v[88:89], v[234:235] op_sel_hi:[1,0]
	v_pk_mul_f32 v[90:91], v[90:91], v[234:235] op_sel_hi:[1,0]
	v_cvt_pk_bf16_f32 v92, v92, v93
	v_cvt_pk_bf16_f32 v93, v94, v95
	v_cvt_pk_bf16_f32 v94, v88, v89
	v_cvt_pk_bf16_f32 v95, v90, v91
	ds_bpermute_b32 v88, v100, v92
	ds_bpermute_b32 v89, v100, v93
	ds_bpermute_b32 v90, v100, v94
	ds_bpermute_b32 v91, v100, v95
	s_waitcnt lgkmcnt(4)
	global_store_dwordx4 v153, v[96:99], s[2:3] nt
	v_add_u32_e32 v153, s0, v153
	v_pk_mul_f32 v[84:85], v[84:85], v[234:235] op_sel_hi:[1,0]
	v_pk_mul_f32 v[86:87], v[86:87], v[234:235] op_sel_hi:[1,0]
	v_pk_mul_f32 v[80:81], v[80:81], v[234:235] op_sel_hi:[1,0]
	v_pk_mul_f32 v[82:83], v[82:83], v[234:235] op_sel_hi:[1,0]
	v_cvt_pk_bf16_f32 v84, v84, v85
	v_cvt_pk_bf16_f32 v85, v86, v87
	v_cvt_pk_bf16_f32 v86, v80, v81
	v_cvt_pk_bf16_f32 v87, v82, v83
	ds_bpermute_b32 v80, v100, v84
	ds_bpermute_b32 v81, v100, v85
	ds_bpermute_b32 v82, v100, v86
	ds_bpermute_b32 v83, v100, v87
	s_waitcnt lgkmcnt(4)
	global_store_dwordx4 v152, v[88:91], s[2:3] nt
	v_add_u32_e32 v152, s0, v152
	v_fmamk_f32 v234, v239, 0x3a800000, v207
	v_rsq_f32_e32 v234, v234
	s_nop 0
	v_mul_f32_e32 v234, s36, v234
	v_pk_mul_f32 v[76:77], v[76:77], v[234:235] op_sel_hi:[1,0]
	v_pk_mul_f32 v[78:79], v[78:79], v[234:235] op_sel_hi:[1,0]
	v_pk_mul_f32 v[72:73], v[72:73], v[234:235] op_sel_hi:[1,0]
	v_pk_mul_f32 v[74:75], v[74:75], v[234:235] op_sel_hi:[1,0]
	v_cvt_pk_bf16_f32 v76, v76, v77
	v_cvt_pk_bf16_f32 v77, v78, v79
	v_cvt_pk_bf16_f32 v78, v72, v73
	v_cvt_pk_bf16_f32 v79, v74, v75
	ds_bpermute_b32 v72, v100, v76
	ds_bpermute_b32 v73, v100, v77
	ds_bpermute_b32 v74, v100, v78
	ds_bpermute_b32 v75, v100, v79
	s_waitcnt lgkmcnt(4)
	global_store_dwordx4 v153, v[80:83], s[2:3] nt
	v_add_u32_e32 v153, s0, v153
	v_pk_mul_f32 v[68:69], v[68:69], v[234:235] op_sel_hi:[1,0]
	v_pk_mul_f32 v[70:71], v[70:71], v[234:235] op_sel_hi:[1,0]
	v_pk_mul_f32 v[64:65], v[64:65], v[234:235] op_sel_hi:[1,0]
	v_pk_mul_f32 v[66:67], v[66:67], v[234:235] op_sel_hi:[1,0]
	v_cvt_pk_bf16_f32 v68, v68, v69
	v_cvt_pk_bf16_f32 v69, v70, v71
	v_cvt_pk_bf16_f32 v70, v64, v65
	v_cvt_pk_bf16_f32 v71, v66, v67
	ds_bpermute_b32 v64, v100, v68
	ds_bpermute_b32 v65, v100, v69
	ds_bpermute_b32 v66, v100, v70
	ds_bpermute_b32 v67, v100, v71
	s_waitcnt lgkmcnt(4)
	global_store_dwordx4 v152, v[72:75], s[2:3] nt
	v_add_u32_e32 v152, s0, v152
	s_waitcnt lgkmcnt(0)
	global_store_dwordx4 v153, v[64:67], s[2:3] nt
	s_waitcnt vmcnt(16)
	s_waitcnt lgkmcnt(0)
	s_barrier
	s_setprio 1
	s_waitcnt lgkmcnt(0)
	v_mfma_f32_16x16x32_bf16 v[126:129], v[144:147], v[182:185], 0
	v_and_b32_e32 v100, 3, v224
	v_lshlrev_b32_e32 v100, 6, v100
	v_and_or_b32 v100, v224, 60, v100
	v_mov_b32_e32 v236, v247
	v_mfma_f32_16x16x32_bf16 v[122:125], v[158:161], v[182:185], 0
	v_add_u32_e32 v237, s32, v247
	v_fmamk_f32 v230, v240, 0x3a800000, v207
	v_rsq_f32_e32 v230, v230
	s_nop 0
	v_mfma_f32_16x16x32_bf16 v[110:113], v[144:147], v[190:193], 0
	v_mul_f32_e32 v230, s36, v230
	v_pk_mul_f32 v[60:61], v[60:61], v[230:231] op_sel_hi:[1,0]
	v_pk_mul_f32 v[62:63], v[62:63], v[230:231] op_sel_hi:[1,0]
	v_pk_mul_f32 v[56:57], v[56:57], v[230:231] op_sel_hi:[1,0]
	v_pk_mul_f32 v[58:59], v[58:59], v[230:231] op_sel_hi:[1,0]
	v_mfma_f32_16x16x32_bf16 v[106:109], v[158:161], v[190:193], 0
	v_cvt_pk_bf16_f32 v60, v60, v61
	v_cvt_pk_bf16_f32 v61, v62, v63
	v_cvt_pk_bf16_f32 v62, v56, v57
	v_cvt_pk_bf16_f32 v63, v58, v59
	v_mfma_f32_16x16x32_bf16 v[92:95], v[144:147], v[198:201], 0
	ds_bpermute_b32 v56, v100, v60
	ds_bpermute_b32 v57, v100, v61
	ds_bpermute_b32 v58, v100, v62
	ds_bpermute_b32 v59, v100, v63
	v_mfma_f32_16x16x32_bf16 v[88:91], v[158:161], v[198:201], 0
	v_pk_mul_f32 v[52:53], v[52:53], v[230:231] op_sel_hi:[1,0]
	v_pk_mul_f32 v[54:55], v[54:55], v[230:231] op_sel_hi:[1,0]
	v_pk_mul_f32 v[48:49], v[48:49], v[230:231] op_sel_hi:[1,0]
	v_pk_mul_f32 v[50:51], v[50:51], v[230:231] op_sel_hi:[1,0]
	v_cvt_pk_bf16_f32 v52, v52, v53
	v_mfma_f32_16x16x32_bf16 v[76:79], v[144:147], v[208:211], 0
	v_cvt_pk_bf16_f32 v53, v54, v55
	v_cvt_pk_bf16_f32 v54, v48, v49
	v_cvt_pk_bf16_f32 v55, v50, v51
	ds_bpermute_b32 v48, v100, v52
	v_mfma_f32_16x16x32_bf16 v[72:75], v[158:161], v[208:211], 0
	ds_bpermute_b32 v49, v100, v53
	ds_bpermute_b32 v50, v100, v54
	ds_bpermute_b32 v51, v100, v55
	s_waitcnt lgkmcnt(4)
	global_store_dwordx4 v236, v[56:59], s[90:91] nt
	v_mfma_f32_16x16x32_bf16 v[126:129], v[148:151], v[186:189], v[126:129]
	v_add_u32_e32 v236, s0, v236
	v_fmamk_f32 v230, v244, 0x3a800000, v207
	v_rsq_f32_e32 v230, v230
	s_nop 0
	v_mfma_f32_16x16x32_bf16 v[122:125], v[162:165], v[186:189], v[122:125]
	v_mul_f32_e32 v230, s36, v230
	v_pk_mul_f32 v[44:45], v[44:45], v[230:231] op_sel_hi:[1,0]
	v_pk_mul_f32 v[46:47], v[46:47], v[230:231] op_sel_hi:[1,0]
	v_pk_mul_f32 v[40:41], v[40:41], v[230:231] op_sel_hi:[1,0]
	v_mfma_f32_16x16x32_bf16 v[110:113], v[148:151], v[194:197], v[110:113]
	v_pk_mul_f32 v[42:43], v[42:43], v[230:231] op_sel_hi:[1,0]
	v_cvt_pk_bf16_f32 v44, v44, v45
	v_cvt_pk_bf16_f32 v45, v46, v47
	v_cvt_pk_bf16_f32 v46, v40, v41
	v_cvt_pk_bf16_f32 v47, v42, v43
	v_mfma_f32_16x16x32_bf16 v[106:109], v[162:165], v[194:197], v[106:109]
	ds_bpermute_b32 v40, v100, v44
	ds_bpermute_b32 v41, v100, v45
	ds_bpermute_b32 v42, v100, v46
	ds_bpermute_b32 v43, v100, v47
	v_mfma_f32_16x16x32_bf16 v[92:95], v[148:151], v[202:205], v[92:95]
	s_waitcnt lgkmcnt(4)
	global_store_dwordx4 v237, v[48:51], s[90:91] nt
	v_add_u32_e32 v237, s0, v237
	v_pk_mul_f32 v[36:37], v[36:37], v[230:231] op_sel_hi:[1,0]
	v_mfma_f32_16x16x32_bf16 v[88:91], v[162:165], v[202:205], v[88:91]
	v_pk_mul_f32 v[38:39], v[38:39], v[230:231] op_sel_hi:[1,0]
	v_pk_mul_f32 v[32:33], v[32:33], v[230:231] op_sel_hi:[1,0]
	v_pk_mul_f32 v[34:35], v[34:35], v[230:231] op_sel_hi:[1,0]
	v_cvt_pk_bf16_f32 v36, v36, v37
	v_cvt_pk_bf16_f32 v37, v38, v39
	v_mfma_f32_16x16x32_bf16 v[76:79], v[148:151], v[226:229], v[76:79]
	v_cvt_pk_bf16_f32 v38, v32, v33
	v_cvt_pk_bf16_f32 v39, v34, v35
	ds_bpermute_b32 v32, v100, v36
	ds_bpermute_b32 v33, v100, v37
	v_mfma_f32_16x16x32_bf16 v[72:75], v[162:165], v[226:229], v[72:75]
	ds_bpermute_b32 v34, v100, v38
	ds_bpermute_b32 v35, v100, v39
	s_waitcnt lgkmcnt(4)
	global_store_dwordx4 v236, v[40:43], s[90:91] nt
	v_add_u32_e32 v236, s0, v236
	s_setprio 0
	s_setprio 1
	v_mfma_f32_16x16x32_bf16 v[118:121], v[166:169], v[182:185], 0
	v_fmamk_f32 v230, v245, 0x3a800000, v207
	v_rsq_f32_e32 v230, v230
	s_nop 0
	v_mul_f32_e32 v230, s36, v230
	v_mfma_f32_16x16x32_bf16 v[114:117], v[174:177], v[182:185], 0
	v_pk_mul_f32 v[28:29], v[28:29], v[230:231] op_sel_hi:[1,0]
	v_pk_mul_f32 v[30:31], v[30:31], v[230:231] op_sel_hi:[1,0]
	v_pk_mul_f32 v[24:25], v[24:25], v[230:231] op_sel_hi:[1,0]
	v_pk_mul_f32 v[26:27], v[26:27], v[230:231] op_sel_hi:[1,0]
	v_mfma_f32_16x16x32_bf16 v[102:105], v[166:169], v[190:193], 0
	v_cvt_pk_bf16_f32 v28, v28, v29
	v_cvt_pk_bf16_f32 v29, v30, v31
	v_cvt_pk_bf16_f32 v30, v24, v25
	v_cvt_pk_bf16_f32 v31, v26, v27
	ds_bpermute_b32 v24, v100, v28
	v_mfma_f32_16x16x32_bf16 v[96:99], v[174:177], v[190:193], 0
	ds_bpermute_b32 v25, v100, v29
	ds_bpermute_b32 v26, v100, v30
	ds_bpermute_b32 v27, v100, v31
	s_waitcnt lgkmcnt(4)
	v_mfma_f32_16x16x32_bf16 v[84:87], v[166:169], v[198:201], 0
	global_store_dwordx4 v237, v[32:35], s[90:91] nt
	v_add_u32_e32 v237, s0, v237
	v_pk_mul_f32 v[20:21], v[20:21], v[230:231] op_sel_hi:[1,0]
	v_pk_mul_f32 v[22:23], v[22:23], v[230:231] op_sel_hi:[1,0]
	v_mfma_f32_16x16x32_bf16 v[80:83], v[174:177], v[198:201], 0
	v_pk_mul_f32 v[16:17], v[16:17], v[230:231] op_sel_hi:[1,0]
	v_pk_mul_f32 v[18:19], v[18:19], v[230:231] op_sel_hi:[1,0]
	v_cvt_pk_bf16_f32 v20, v20, v21
	v_cvt_pk_bf16_f32 v21, v22, v23
	v_cvt_pk_bf16_f32 v22, v16, v17
	v_mfma_f32_16x16x32_bf16 v[68:71], v[166:169], v[208:211], 0
	v_cvt_pk_bf16_f32 v23, v18, v19
	ds_bpermute_b32 v16, v100, v20
	ds_bpermute_b32 v17, v100, v21
	ds_bpermute_b32 v18, v100, v22
	v_mfma_f32_16x16x32_bf16 v[64:67], v[174:177], v[208:211], 0
	ds_bpermute_b32 v19, v100, v23
	s_waitcnt lgkmcnt(4)
	global_store_dwordx4 v236, v[24:27], s[90:91] nt
	v_add_u32_e32 v236, s0, v236
	v_fmamk_f32 v230, v246, 0x3a800000, v207
	v_mfma_f32_16x16x32_bf16 v[118:121], v[170:173], v[186:189], v[118:121]
	v_rsq_f32_e32 v230, v230
	s_nop 0
	v_mul_f32_e32 v230, s36, v230
	v_pk_mul_f32 v[12:13], v[12:13], v[230:231] op_sel_hi:[1,0]
	v_mfma_f32_16x16x32_bf16 v[114:117], v[178:181], v[186:189], v[114:117]
	v_pk_mul_f32 v[14:15], v[14:15], v[230:231] op_sel_hi:[1,0]
	v_pk_mul_f32 v[8:9], v[8:9], v[230:231] op_sel_hi:[1,0]
	v_pk_mul_f32 v[10:11], v[10:11], v[230:231] op_sel_hi:[1,0]
	v_cvt_pk_bf16_f32 v12, v12, v13
	v_mfma_f32_16x16x32_bf16 v[102:105], v[170:173], v[194:197], v[102:105]
	v_cvt_pk_bf16_f32 v13, v14, v15
	v_cvt_pk_bf16_f32 v14, v8, v9
	v_cvt_pk_bf16_f32 v15, v10, v11
	ds_bpermute_b32 v8, v100, v12
	ds_bpermute_b32 v9, v100, v13
	v_mfma_f32_16x16x32_bf16 v[96:99], v[178:181], v[194:197], v[96:99]
	ds_bpermute_b32 v10, v100, v14
	ds_bpermute_b32 v11, v100, v15
	s_waitcnt lgkmcnt(4)
	global_store_dwordx4 v237, v[16:19], s[90:91] nt
	v_mfma_f32_16x16x32_bf16 v[84:87], v[170:173], v[202:205], v[84:87]
	v_add_u32_e32 v237, s0, v237
	v_pk_mul_f32 v[4:5], v[4:5], v[230:231] op_sel_hi:[1,0]
	v_pk_mul_f32 v[6:7], v[6:7], v[230:231] op_sel_hi:[1,0]
	v_pk_mul_f32 v[0:1], v[0:1], v[230:231] op_sel_hi:[1,0]
	v_mfma_f32_16x16x32_bf16 v[80:83], v[178:181], v[202:205], v[80:83]
	v_pk_mul_f32 v[2:3], v[2:3], v[230:231] op_sel_hi:[1,0]
	v_cvt_pk_bf16_f32 v4, v4, v5
	v_cvt_pk_bf16_f32 v5, v6, v7
	v_cvt_pk_bf16_f32 v6, v0, v1
	v_cvt_pk_bf16_f32 v7, v2, v3
	v_mfma_f32_16x16x32_bf16 v[68:71], v[170:173], v[226:229], v[68:71]
	ds_bpermute_b32 v0, v100, v4
	ds_bpermute_b32 v1, v100, v5
	ds_bpermute_b32 v2, v100, v6
	ds_bpermute_b32 v3, v100, v7
	v_mfma_f32_16x16x32_bf16 v[64:67], v[178:181], v[226:229], v[64:67]
	s_waitcnt lgkmcnt(4)
	global_store_dwordx4 v236, v[8:11], s[90:91] nt
	v_add_u32_e32 v236, s0, v236
	s_waitcnt lgkmcnt(0)
	global_store_dwordx4 v237, v[0:3], s[90:91] nt
	s_setprio 0
	s_barrier
	s_add_i32 s33, s33, s34
	v_lshl_add_u64 v[152:153], s[14:15], 0, v[132:133]
	s_mov_b32 m0, s33
	ds_read_b128 v[182:185], v156 offset:16384
	ds_read_b128 v[186:189], v156 offset:17408
	ds_read_b128 v[190:193], v156 offset:18432
	ds_read_b128 v[194:197], v156 offset:19456
	ds_read_b128 v[198:201], v156 offset:20480
	ds_read_b128 v[202:205], v156 offset:21504
	ds_read_b128 v[208:211], v156 offset:22528
	ds_read_b128 v[226:229], v156 offset:23552
	global_load_lds_dwordx4 v[152:153], off
	s_add_i32 m0, s33, 0x2000
	s_add_u32 s80, s14, 0x40000
	v_lshl_add_u64 v[212:213], s[14:15], 0, v[136:137]
	s_addc_u32 s81, s15, 0
	s_add_i32 s1, s1, s34
	global_load_lds_dwordx4 v[212:213], off
	v_lshl_add_u64 v[230:231], s[80:81], 0, v[132:133]
	s_mov_b32 m0, s1
	v_lshl_add_u64 v[232:233], s[28:29], 0, v[134:135]
	global_load_lds_dwordx4 v[230:231], off
	v_lshl_add_u64 v[230:231], s[80:81], 0, v[136:137]
	s_add_i32 m0, s1, 0x2000
	s_nop 0
	global_load_lds_dwordx4 v[230:231], off
	v_lshl_add_u64 v[230:231], s[28:29], 0, v[130:131]
	s_mov_b32 m0, s41
	s_nop 0
	global_load_lds_dwordx4 v[230:231], off
	s_mov_b32 m0, s60
	s_nop 0
	global_load_lds_dwordx4 v[232:233], off
	s_lshl_b32 s46, s40, 8
	s_add_i32 s46, s46, s84
	v_or_b32_e32 v100, s46, v139
	v_lshlrev_b32_e32 v100, 2, v100
	global_load_dword v236, v100, s[66:67]
	global_load_dword v237, v100, s[66:67] offset:64
	global_load_dword v238, v100, s[66:67] offset:128
	global_load_dword v239, v100, s[66:67] offset:192
	global_load_dword v240, v100, s[66:67] offset:512
	global_load_dword v244, v100, s[66:67] offset:576
	global_load_dword v245, v100, s[66:67] offset:640
	global_load_dword v246, v100, s[66:67] offset:704
	s_waitcnt vmcnt(32)
	s_waitcnt lgkmcnt(0)
	s_barrier
	s_setprio 1
	s_waitcnt lgkmcnt(0)
	v_mfma_f32_16x16x32_bf16 v[60:63], v[144:147], v[182:185], 0
	v_mfma_f32_16x16x32_bf16 v[56:59], v[158:161], v[182:185], 0
	v_mfma_f32_16x16x32_bf16 v[44:47], v[144:147], v[190:193], 0
	v_mfma_f32_16x16x32_bf16 v[40:43], v[158:161], v[190:193], 0
	v_mfma_f32_16x16x32_bf16 v[28:31], v[144:147], v[198:201], 0
	v_mfma_f32_16x16x32_bf16 v[24:27], v[158:161], v[198:201], 0
	v_mfma_f32_16x16x32_bf16 v[12:15], v[144:147], v[208:211], 0
	v_mfma_f32_16x16x32_bf16 v[8:11], v[158:161], v[208:211], 0
	v_mfma_f32_16x16x32_bf16 v[60:63], v[148:151], v[186:189], v[60:63]
	v_mfma_f32_16x16x32_bf16 v[56:59], v[162:165], v[186:189], v[56:59]
	v_mfma_f32_16x16x32_bf16 v[44:47], v[148:151], v[194:197], v[44:47]
	v_mfma_f32_16x16x32_bf16 v[40:43], v[162:165], v[194:197], v[40:43]
	v_mfma_f32_16x16x32_bf16 v[28:31], v[148:151], v[202:205], v[28:31]
	v_mfma_f32_16x16x32_bf16 v[24:27], v[162:165], v[202:205], v[24:27]
	v_mfma_f32_16x16x32_bf16 v[12:15], v[148:151], v[226:229], v[12:15]
	v_mfma_f32_16x16x32_bf16 v[8:11], v[162:165], v[226:229], v[8:11]
	s_setprio 0
	s_setprio 1
	v_mfma_f32_16x16x32_bf16 v[52:55], v[166:169], v[182:185], 0
	v_mfma_f32_16x16x32_bf16 v[48:51], v[174:177], v[182:185], 0
	v_mfma_f32_16x16x32_bf16 v[36:39], v[166:169], v[190:193], 0
	v_mfma_f32_16x16x32_bf16 v[32:35], v[174:177], v[190:193], 0
	v_mfma_f32_16x16x32_bf16 v[20:23], v[166:169], v[198:201], 0
	v_mfma_f32_16x16x32_bf16 v[16:19], v[174:177], v[198:201], 0
	v_mfma_f32_16x16x32_bf16 v[4:7], v[166:169], v[208:211], 0
	v_mfma_f32_16x16x32_bf16 v[0:3], v[174:177], v[208:211], 0
	v_mfma_f32_16x16x32_bf16 v[52:55], v[170:173], v[186:189], v[52:55]
	v_mfma_f32_16x16x32_bf16 v[48:51], v[178:181], v[186:189], v[48:51]
	v_mfma_f32_16x16x32_bf16 v[36:39], v[170:173], v[194:197], v[36:39]
	v_mfma_f32_16x16x32_bf16 v[32:35], v[178:181], v[194:197], v[32:35]
	v_mfma_f32_16x16x32_bf16 v[20:23], v[170:173], v[202:205], v[20:23]
	v_mfma_f32_16x16x32_bf16 v[16:19], v[178:181], v[202:205], v[16:19]
	v_mfma_f32_16x16x32_bf16 v[4:7], v[170:173], v[226:229], v[4:7]
	v_mfma_f32_16x16x32_bf16 v[0:3], v[178:181], v[226:229], v[0:3]
	s_setprio 0
	s_barrier
	s_add_i32 s1, 0, 0x18000
	v_add_u32_e32 v100, s1, v154
	s_add_i32 s33, 0, 0x1c000
	ds_read_b128 v[144:147], v100
	ds_read_b128 v[148:151], v100 offset:1024
	ds_read_b128 v[158:161], v100 offset:2048
	ds_read_b128 v[162:165], v100 offset:3072
	v_add_u32_e32 v100, s33, v154
	ds_read_b128 v[166:169], v100
	ds_read_b128 v[170:173], v100 offset:1024
	ds_read_b128 v[174:177], v100 offset:2048
	ds_read_b128 v[178:181], v100 offset:3072
	s_add_u32 s28, s28, 0x40000
	s_addc_u32 s29, s29, 0
	s_mov_b32 m0, s61
	v_lshl_add_u64 v[234:235], s[28:29], 0, v[130:131]
	ds_read_b128 v[182:185], v156 offset:32768
	ds_read_b128 v[186:189], v156 offset:33792
	ds_read_b128 v[190:193], v156 offset:34816
	ds_read_b128 v[194:197], v156 offset:35840
	ds_read_b128 v[198:201], v156 offset:36864
	ds_read_b128 v[202:205], v156 offset:37888
	ds_read_b128 v[208:211], v156 offset:38912
	ds_read_b128 v[226:229], v156 offset:39936
	global_load_lds_dwordx4 v[234:235], off
	v_lshl_add_u64 v[234:235], s[28:29], 0, v[134:135]
	s_mov_b32 m0, s69
	s_nop 0
	global_load_lds_dwordx4 v[234:235], off
	s_waitcnt vmcnt(32)
	s_waitcnt lgkmcnt(0)
	s_barrier
	s_setprio 1
	s_waitcnt lgkmcnt(0)
	v_mfma_f32_16x16x32_bf16 v[126:129], v[144:147], v[182:185], v[126:129]
	v_mfma_f32_16x16x32_bf16 v[122:125], v[158:161], v[182:185], v[122:125]
	v_mfma_f32_16x16x32_bf16 v[110:113], v[144:147], v[190:193], v[110:113]
	v_mfma_f32_16x16x32_bf16 v[106:109], v[158:161], v[190:193], v[106:109]
	v_mfma_f32_16x16x32_bf16 v[92:95], v[144:147], v[198:201], v[92:95]
	v_mfma_f32_16x16x32_bf16 v[88:91], v[158:161], v[198:201], v[88:91]
	v_mfma_f32_16x16x32_bf16 v[76:79], v[144:147], v[208:211], v[76:79]
	v_mfma_f32_16x16x32_bf16 v[72:75], v[158:161], v[208:211], v[72:75]
	v_mfma_f32_16x16x32_bf16 v[126:129], v[148:151], v[186:189], v[126:129]
	v_mfma_f32_16x16x32_bf16 v[122:125], v[162:165], v[186:189], v[122:125]
	v_mfma_f32_16x16x32_bf16 v[110:113], v[148:151], v[194:197], v[110:113]
	v_mfma_f32_16x16x32_bf16 v[106:109], v[162:165], v[194:197], v[106:109]
	v_mfma_f32_16x16x32_bf16 v[92:95], v[148:151], v[202:205], v[92:95]
	v_mfma_f32_16x16x32_bf16 v[88:91], v[162:165], v[202:205], v[88:91]
	v_mfma_f32_16x16x32_bf16 v[76:79], v[148:151], v[226:229], v[76:79]
	v_mfma_f32_16x16x32_bf16 v[72:75], v[162:165], v[226:229], v[72:75]
	s_setprio 0
	s_setprio 1
	v_mfma_f32_16x16x32_bf16 v[118:121], v[166:169], v[182:185], v[118:121]
	v_mfma_f32_16x16x32_bf16 v[114:117], v[174:177], v[182:185], v[114:117]
	v_mfma_f32_16x16x32_bf16 v[102:105], v[166:169], v[190:193], v[102:105]
	v_mfma_f32_16x16x32_bf16 v[96:99], v[174:177], v[190:193], v[96:99]
	v_mfma_f32_16x16x32_bf16 v[84:87], v[166:169], v[198:201], v[84:87]
	v_mfma_f32_16x16x32_bf16 v[80:83], v[174:177], v[198:201], v[80:83]
	v_mfma_f32_16x16x32_bf16 v[68:71], v[166:169], v[208:211], v[68:71]
	v_mfma_f32_16x16x32_bf16 v[64:67], v[174:177], v[208:211], v[64:67]
	v_mfma_f32_16x16x32_bf16 v[118:121], v[170:173], v[186:189], v[118:121]
	v_mfma_f32_16x16x32_bf16 v[114:117], v[178:181], v[186:189], v[114:117]
	v_mfma_f32_16x16x32_bf16 v[102:105], v[170:173], v[194:197], v[102:105]
	v_mfma_f32_16x16x32_bf16 v[96:99], v[178:181], v[194:197], v[96:99]
	v_mfma_f32_16x16x32_bf16 v[84:87], v[170:173], v[202:205], v[84:87]
	v_mfma_f32_16x16x32_bf16 v[80:83], v[178:181], v[202:205], v[80:83]
	v_mfma_f32_16x16x32_bf16 v[68:71], v[170:173], v[226:229], v[68:71]
	v_mfma_f32_16x16x32_bf16 v[64:67], v[178:181], v[226:229], v[64:67]
	s_setprio 0
	s_barrier
	s_add_i32 s1, s1, s34
	v_lshl_add_u64 v[152:153], v[152:153], 0, s[86:87]
	s_mov_b32 m0, s1
	ds_read_b128 v[182:185], v156 offset:49152
	ds_read_b128 v[186:189], v156 offset:50176
	ds_read_b128 v[190:193], v156 offset:51200
	ds_read_b128 v[194:197], v156 offset:52224
	ds_read_b128 v[198:201], v156 offset:53248
	ds_read_b128 v[202:205], v156 offset:54272
	ds_read_b128 v[208:211], v156 offset:55296
	ds_read_b128 v[226:229], v156 offset:56320
	global_load_lds_dwordx4 v[152:153], off
	s_add_i32 m0, s1, 0x2000
	s_add_u32 s14, s14, 0x40080
	v_lshl_add_u64 v[152:153], v[212:213], 0, s[86:87]
	s_addc_u32 s15, s15, 0
	s_add_i32 s1, s33, s34
	global_load_lds_dwordx4 v[152:153], off
	v_lshl_add_u64 v[152:153], s[14:15], 0, v[132:133]
	s_mov_b32 m0, s1
	s_nop 0
	global_load_lds_dwordx4 v[152:153], off
	v_lshl_add_u64 v[152:153], s[14:15], 0, v[136:137]
	s_add_i32 m0, s1, 0x2000
	s_nop 0
	global_load_lds_dwordx4 v[152:153], off
	v_lshl_add_u64 v[152:153], v[230:231], 0, s[86:87]
	s_mov_b32 m0, s89
	s_nop 0
	global_load_lds_dwordx4 v[152:153], off
	v_lshl_add_u64 v[152:153], v[232:233], 0, s[86:87]
	s_mov_b32 m0, s92
	s_nop 0
	global_load_lds_dwordx4 v[152:153], off
	s_waitcnt vmcnt(16)
	s_waitcnt lgkmcnt(0)
	s_barrier
	s_setprio 1
	s_waitcnt lgkmcnt(0)
	v_mfma_f32_16x16x32_bf16 v[60:63], v[144:147], v[182:185], v[60:63]
	v_mfma_f32_16x16x32_bf16 v[56:59], v[158:161], v[182:185], v[56:59]
	v_mfma_f32_16x16x32_bf16 v[44:47], v[144:147], v[190:193], v[44:47]
	v_mfma_f32_16x16x32_bf16 v[40:43], v[158:161], v[190:193], v[40:43]
	v_mfma_f32_16x16x32_bf16 v[28:31], v[144:147], v[198:201], v[28:31]
	v_mfma_f32_16x16x32_bf16 v[24:27], v[158:161], v[198:201], v[24:27]
	v_mfma_f32_16x16x32_bf16 v[12:15], v[144:147], v[208:211], v[12:15]
	v_mfma_f32_16x16x32_bf16 v[8:11], v[158:161], v[208:211], v[8:11]
	v_mfma_f32_16x16x32_bf16 v[60:63], v[148:151], v[186:189], v[60:63]
	v_mfma_f32_16x16x32_bf16 v[56:59], v[162:165], v[186:189], v[56:59]
	v_mfma_f32_16x16x32_bf16 v[44:47], v[148:151], v[194:197], v[44:47]
	v_mfma_f32_16x16x32_bf16 v[40:43], v[162:165], v[194:197], v[40:43]
	v_mfma_f32_16x16x32_bf16 v[28:31], v[148:151], v[202:205], v[28:31]
	v_mfma_f32_16x16x32_bf16 v[24:27], v[162:165], v[202:205], v[24:27]
	v_mfma_f32_16x16x32_bf16 v[12:15], v[148:151], v[226:229], v[12:15]
	v_mfma_f32_16x16x32_bf16 v[8:11], v[162:165], v[226:229], v[8:11]
	s_setprio 0
	s_setprio 1
	v_mfma_f32_16x16x32_bf16 v[52:55], v[166:169], v[182:185], v[52:55]
	v_mfma_f32_16x16x32_bf16 v[48:51], v[174:177], v[182:185], v[48:51]
	v_mfma_f32_16x16x32_bf16 v[36:39], v[166:169], v[190:193], v[36:39]
	v_mfma_f32_16x16x32_bf16 v[32:35], v[174:177], v[190:193], v[32:35]
	v_mfma_f32_16x16x32_bf16 v[20:23], v[166:169], v[198:201], v[20:23]
	v_mfma_f32_16x16x32_bf16 v[16:19], v[174:177], v[198:201], v[16:19]
	v_mfma_f32_16x16x32_bf16 v[4:7], v[166:169], v[208:211], v[4:7]
	v_mfma_f32_16x16x32_bf16 v[0:3], v[174:177], v[208:211], v[0:3]
	v_mfma_f32_16x16x32_bf16 v[52:55], v[170:173], v[186:189], v[52:55]
	v_mfma_f32_16x16x32_bf16 v[48:51], v[178:181], v[186:189], v[48:51]
	v_mfma_f32_16x16x32_bf16 v[36:39], v[170:173], v[194:197], v[36:39]
	v_mfma_f32_16x16x32_bf16 v[32:35], v[178:181], v[194:197], v[32:35]
	v_mfma_f32_16x16x32_bf16 v[20:23], v[170:173], v[202:205], v[20:23]
	v_mfma_f32_16x16x32_bf16 v[16:19], v[178:181], v[202:205], v[16:19]
	v_mfma_f32_16x16x32_bf16 v[4:7], v[170:173], v[226:229], v[4:7]
	v_mfma_f32_16x16x32_bf16 v[0:3], v[178:181], v[226:229], v[0:3]
	s_setprio 0
	s_barrier
	s_add_i32 s73, s73, 2
	s_add_u32 s12, s12, 0x100
	s_addc_u32 s13, s13, 0
	s_add_u32 s54, s54, 0x100
	s_addc_u32 s55, s55, 0

.Lmy_b16_addr_i:
	v_and_b32_e32 v145, 3, v224
	v_lshlrev_b32_e32 v145, 6, v145
	v_and_or_b32 v145, v224, 60, v145
	s_add_u32 s28, s10, s14
	s_addc_u32 s29, s11, 0
	s_mul_i32 s15, s12, 3
	s_sub_i32 s13, s13, s15
	s_and_b64 vcc, exec, s[30:31]
	s_cbranch_vccnz .Lmy_b16_norm
	v_fmamk_f32 v158, v236, 0x3a800000, v207
	v_rsq_f32_e32 v158, v158
	s_nop 0
	v_mul_f32_e32 v158, s100, v158
	v_pk_mul_f32 v[126:127], v[126:127], v[158:159] op_sel_hi:[1,0]
	v_pk_mul_f32 v[128:129], v[128:129], v[158:159] op_sel_hi:[1,0]
	v_pk_mul_f32 v[122:123], v[122:123], v[158:159] op_sel_hi:[1,0]
	v_pk_mul_f32 v[124:125], v[124:125], v[158:159] op_sel_hi:[1,0]
	v_cvt_pk_bf16_f32 v146, v126, v127
	v_cvt_pk_bf16_f32 v147, v128, v129
	v_cvt_pk_bf16_f32 v148, v122, v123
	v_cvt_pk_bf16_f32 v149, v124, v125
	ds_bpermute_b32 v168, v145, v146
	ds_bpermute_b32 v169, v145, v147
	ds_bpermute_b32 v170, v145, v148
	ds_bpermute_b32 v171, v145, v149
	v_pk_mul_f32 v[118:119], v[118:119], v[158:159] op_sel_hi:[1,0]
	v_pk_mul_f32 v[120:121], v[120:121], v[158:159] op_sel_hi:[1,0]
	v_pk_mul_f32 v[114:115], v[114:115], v[158:159] op_sel_hi:[1,0]
	v_pk_mul_f32 v[116:117], v[116:117], v[158:159] op_sel_hi:[1,0]
	v_cvt_pk_bf16_f32 v150, v118, v119
	v_cvt_pk_bf16_f32 v151, v120, v121
	v_cvt_pk_bf16_f32 v152, v114, v115
	v_cvt_pk_bf16_f32 v153, v116, v117
	ds_bpermute_b32 v172, v145, v150
	ds_bpermute_b32 v173, v145, v151
	ds_bpermute_b32 v174, v145, v152
	ds_bpermute_b32 v175, v145, v153
	s_waitcnt lgkmcnt(4)
	global_store_dwordx4 v144, v[168:171], s[10:11] nt
	s_add_u32 s54, s10, s12
	s_addc_u32 s55, s11, 0
	s_add_u32 s80, s28, s12
	s_addc_u32 s81, s29, 0
	v_fmamk_f32 v158, v237, 0x3a800000, v207
	v_rsq_f32_e32 v158, v158
	s_nop 0
	v_mul_f32_e32 v158, s100, v158
	v_pk_mul_f32 v[110:111], v[110:111], v[158:159] op_sel_hi:[1,0]
	v_pk_mul_f32 v[112:113], v[112:113], v[158:159] op_sel_hi:[1,0]
	v_pk_mul_f32 v[106:107], v[106:107], v[158:159] op_sel_hi:[1,0]
	v_pk_mul_f32 v[108:109], v[108:109], v[158:159] op_sel_hi:[1,0]
	v_cvt_pk_bf16_f32 v146, v110, v111
	v_cvt_pk_bf16_f32 v147, v112, v113
	v_cvt_pk_bf16_f32 v148, v106, v107
	v_cvt_pk_bf16_f32 v149, v108, v109
	ds_bpermute_b32 v168, v145, v146
	ds_bpermute_b32 v169, v145, v147
	ds_bpermute_b32 v170, v145, v148
	ds_bpermute_b32 v171, v145, v149
	s_waitcnt lgkmcnt(4)
	global_store_dwordx4 v144, v[172:175], s[28:29] nt
	v_pk_mul_f32 v[102:103], v[102:103], v[158:159] op_sel_hi:[1,0]
	v_pk_mul_f32 v[104:105], v[104:105], v[158:159] op_sel_hi:[1,0]
	v_pk_mul_f32 v[96:97], v[96:97], v[158:159] op_sel_hi:[1,0]
	v_pk_mul_f32 v[98:99], v[98:99], v[158:159] op_sel_hi:[1,0]
	v_cvt_pk_bf16_f32 v150, v102, v103
	v_cvt_pk_bf16_f32 v151, v104, v105
	v_cvt_pk_bf16_f32 v152, v96, v97
	v_cvt_pk_bf16_f32 v153, v98, v99
	ds_bpermute_b32 v172, v145, v150
	ds_bpermute_b32 v173, v145, v151
	ds_bpermute_b32 v174, v145, v152
	ds_bpermute_b32 v175, v145, v153
	s_waitcnt lgkmcnt(4)
	global_store_dwordx4 v144, v[168:171], s[54:55] nt
	s_add_u32 s10, s54, s12
	s_addc_u32 s11, s55, 0
	s_add_u32 s28, s80, s12
	s_addc_u32 s29, s81, 0
	v_fmamk_f32 v158, v238, 0x3a800000, v207
	v_rsq_f32_e32 v158, v158
	s_nop 0
	v_mul_f32_e32 v158, s100, v158
	v_pk_mul_f32 v[92:93], v[92:93], v[158:159] op_sel_hi:[1,0]
	v_pk_mul_f32 v[94:95], v[94:95], v[158:159] op_sel_hi:[1,0]
	v_pk_mul_f32 v[88:89], v[88:89], v[158:159] op_sel_hi:[1,0]
	v_pk_mul_f32 v[90:91], v[90:91], v[158:159] op_sel_hi:[1,0]
	v_cvt_pk_bf16_f32 v146, v92, v93
	v_cvt_pk_bf16_f32 v147, v94, v95
	v_cvt_pk_bf16_f32 v148, v88, v89
	v_cvt_pk_bf16_f32 v149, v90, v91
	ds_bpermute_b32 v168, v145, v146
	ds_bpermute_b32 v169, v145, v147
	ds_bpermute_b32 v170, v145, v148
	ds_bpermute_b32 v171, v145, v149
	s_waitcnt lgkmcnt(4)
	global_store_dwordx4 v144, v[172:175], s[80:81] nt
	v_pk_mul_f32 v[84:85], v[84:85], v[158:159] op_sel_hi:[1,0]
	v_pk_mul_f32 v[86:87], v[86:87], v[158:159] op_sel_hi:[1,0]
	v_pk_mul_f32 v[80:81], v[80:81], v[158:159] op_sel_hi:[1,0]
	v_pk_mul_f32 v[82:83], v[82:83], v[158:159] op_sel_hi:[1,0]
	v_cvt_pk_bf16_f32 v150, v84, v85
	v_cvt_pk_bf16_f32 v151, v86, v87
	v_cvt_pk_bf16_f32 v152, v80, v81
	v_cvt_pk_bf16_f32 v153, v82, v83
	ds_bpermute_b32 v172, v145, v150
	ds_bpermute_b32 v173, v145, v151
	ds_bpermute_b32 v174, v145, v152
	ds_bpermute_b32 v175, v145, v153
	s_waitcnt lgkmcnt(4)
	global_store_dwordx4 v144, v[168:171], s[10:11] nt
	s_add_u32 s54, s10, s12
	s_addc_u32 s55, s11, 0
	s_add_u32 s80, s28, s12
	s_addc_u32 s81, s29, 0
	v_fmamk_f32 v158, v239, 0x3a800000, v207
	v_rsq_f32_e32 v158, v158
	s_nop 0
	v_mul_f32_e32 v158, s100, v158
	v_pk_mul_f32 v[76:77], v[76:77], v[158:159] op_sel_hi:[1,0]
	v_pk_mul_f32 v[78:79], v[78:79], v[158:159] op_sel_hi:[1,0]
	v_pk_mul_f32 v[72:73], v[72:73], v[158:159] op_sel_hi:[1,0]
	v_pk_mul_f32 v[74:75], v[74:75], v[158:159] op_sel_hi:[1,0]
	v_cvt_pk_bf16_f32 v146, v76, v77
	v_cvt_pk_bf16_f32 v147, v78, v79
	v_cvt_pk_bf16_f32 v148, v72, v73
	v_cvt_pk_bf16_f32 v149, v74, v75
	ds_bpermute_b32 v168, v145, v146
	ds_bpermute_b32 v169, v145, v147
	ds_bpermute_b32 v170, v145, v148
	ds_bpermute_b32 v171, v145, v149
	s_waitcnt lgkmcnt(4)
	global_store_dwordx4 v144, v[172:175], s[28:29] nt
	v_pk_mul_f32 v[68:69], v[68:69], v[158:159] op_sel_hi:[1,0]
	v_pk_mul_f32 v[70:71], v[70:71], v[158:159] op_sel_hi:[1,0]
	v_pk_mul_f32 v[64:65], v[64:65], v[158:159] op_sel_hi:[1,0]
	v_pk_mul_f32 v[66:67], v[66:67], v[158:159] op_sel_hi:[1,0]
	v_cvt_pk_bf16_f32 v150, v68, v69
	v_cvt_pk_bf16_f32 v151, v70, v71
	v_cvt_pk_bf16_f32 v152, v64, v65
	v_cvt_pk_bf16_f32 v153, v66, v67
	ds_bpermute_b32 v172, v145, v150
	ds_bpermute_b32 v173, v145, v151
	ds_bpermute_b32 v174, v145, v152
	ds_bpermute_b32 v175, v145, v153
	s_waitcnt lgkmcnt(4)
	global_store_dwordx4 v144, v[168:171], s[54:55] nt
	s_add_u32 s10, s54, s13
	s_addc_u32 s11, s55, 0
	s_add_u32 s28, s80, s13
	s_addc_u32 s29, s81, 0
	v_fmamk_f32 v158, v240, 0x3a800000, v207
	v_rsq_f32_e32 v158, v158
	s_nop 0
	v_mul_f32_e32 v158, s100, v158
	v_pk_mul_f32 v[60:61], v[60:61], v[158:159] op_sel_hi:[1,0]
	v_pk_mul_f32 v[62:63], v[62:63], v[158:159] op_sel_hi:[1,0]
	v_pk_mul_f32 v[56:57], v[56:57], v[158:159] op_sel_hi:[1,0]
	v_pk_mul_f32 v[58:59], v[58:59], v[158:159] op_sel_hi:[1,0]
	v_cvt_pk_bf16_f32 v146, v60, v61
	v_cvt_pk_bf16_f32 v147, v62, v63
	v_cvt_pk_bf16_f32 v148, v56, v57
	v_cvt_pk_bf16_f32 v149, v58, v59
	ds_bpermute_b32 v168, v145, v146
	ds_bpermute_b32 v169, v145, v147
	ds_bpermute_b32 v170, v145, v148
	ds_bpermute_b32 v171, v145, v149
	s_waitcnt lgkmcnt(4)
	global_store_dwordx4 v144, v[172:175], s[80:81] nt
	v_pk_mul_f32 v[52:53], v[52:53], v[158:159] op_sel_hi:[1,0]
	v_pk_mul_f32 v[54:55], v[54:55], v[158:159] op_sel_hi:[1,0]
	v_pk_mul_f32 v[48:49], v[48:49], v[158:159] op_sel_hi:[1,0]
	v_pk_mul_f32 v[50:51], v[50:51], v[158:159] op_sel_hi:[1,0]
	v_cvt_pk_bf16_f32 v150, v52, v53
	v_cvt_pk_bf16_f32 v151, v54, v55
	v_cvt_pk_bf16_f32 v152, v48, v49
	v_cvt_pk_bf16_f32 v153, v50, v51
	ds_bpermute_b32 v172, v145, v150
	ds_bpermute_b32 v173, v145, v151
	ds_bpermute_b32 v174, v145, v152
	ds_bpermute_b32 v175, v145, v153
	s_waitcnt lgkmcnt(4)
	global_store_dwordx4 v144, v[168:171], s[10:11] nt
	s_add_u32 s54, s10, s12
	s_addc_u32 s55, s11, 0
	s_add_u32 s80, s28, s12
	s_addc_u32 s81, s29, 0
	v_fmamk_f32 v158, v244, 0x3a800000, v207
	v_rsq_f32_e32 v158, v158
	s_nop 0
	v_mul_f32_e32 v158, s100, v158
	v_pk_mul_f32 v[44:45], v[44:45], v[158:159] op_sel_hi:[1,0]
	v_pk_mul_f32 v[46:47], v[46:47], v[158:159] op_sel_hi:[1,0]
	v_pk_mul_f32 v[40:41], v[40:41], v[158:159] op_sel_hi:[1,0]
	v_pk_mul_f32 v[42:43], v[42:43], v[158:159] op_sel_hi:[1,0]
	v_cvt_pk_bf16_f32 v146, v44, v45
	v_cvt_pk_bf16_f32 v147, v46, v47
	v_cvt_pk_bf16_f32 v148, v40, v41
	v_cvt_pk_bf16_f32 v149, v42, v43
	ds_bpermute_b32 v168, v145, v146
	ds_bpermute_b32 v169, v145, v147
	ds_bpermute_b32 v170, v145, v148
	ds_bpermute_b32 v171, v145, v149
	s_waitcnt lgkmcnt(4)
	global_store_dwordx4 v144, v[172:175], s[28:29] nt
	v_pk_mul_f32 v[36:37], v[36:37], v[158:159] op_sel_hi:[1,0]
	v_pk_mul_f32 v[38:39], v[38:39], v[158:159] op_sel_hi:[1,0]
	v_pk_mul_f32 v[32:33], v[32:33], v[158:159] op_sel_hi:[1,0]
	v_pk_mul_f32 v[34:35], v[34:35], v[158:159] op_sel_hi:[1,0]
	v_cvt_pk_bf16_f32 v150, v36, v37
	v_cvt_pk_bf16_f32 v151, v38, v39
	v_cvt_pk_bf16_f32 v152, v32, v33
	v_cvt_pk_bf16_f32 v153, v34, v35
	ds_bpermute_b32 v172, v145, v150
	ds_bpermute_b32 v173, v145, v151
	ds_bpermute_b32 v174, v145, v152
	ds_bpermute_b32 v175, v145, v153
	s_waitcnt lgkmcnt(4)
	global_store_dwordx4 v144, v[168:171], s[54:55] nt
	s_add_u32 s10, s54, s12
	s_addc_u32 s11, s55, 0
	s_add_u32 s28, s80, s12
	s_addc_u32 s29, s81, 0
	v_fmamk_f32 v158, v245, 0x3a800000, v207
	v_rsq_f32_e32 v158, v158
	s_nop 0
	v_mul_f32_e32 v158, s100, v158
	v_pk_mul_f32 v[28:29], v[28:29], v[158:159] op_sel_hi:[1,0]
	v_pk_mul_f32 v[30:31], v[30:31], v[158:159] op_sel_hi:[1,0]
	v_pk_mul_f32 v[24:25], v[24:25], v[158:159] op_sel_hi:[1,0]
	v_pk_mul_f32 v[26:27], v[26:27], v[158:159] op_sel_hi:[1,0]
	v_cvt_pk_bf16_f32 v146, v28, v29
	v_cvt_pk_bf16_f32 v147, v30, v31
	v_cvt_pk_bf16_f32 v148, v24, v25
	v_cvt_pk_bf16_f32 v149, v26, v27
	ds_bpermute_b32 v168, v145, v146
	ds_bpermute_b32 v169, v145, v147
	ds_bpermute_b32 v170, v145, v148
	ds_bpermute_b32 v171, v145, v149
	s_waitcnt lgkmcnt(4)
	global_store_dwordx4 v144, v[172:175], s[80:81] nt
	v_pk_mul_f32 v[20:21], v[20:21], v[158:159] op_sel_hi:[1,0]
	v_pk_mul_f32 v[22:23], v[22:23], v[158:159] op_sel_hi:[1,0]
	v_pk_mul_f32 v[16:17], v[16:17], v[158:159] op_sel_hi:[1,0]
	v_pk_mul_f32 v[18:19], v[18:19], v[158:159] op_sel_hi:[1,0]
	v_cvt_pk_bf16_f32 v150, v20, v21
	v_cvt_pk_bf16_f32 v151, v22, v23
	v_cvt_pk_bf16_f32 v152, v16, v17
	v_cvt_pk_bf16_f32 v153, v18, v19
	ds_bpermute_b32 v172, v145, v150
	ds_bpermute_b32 v173, v145, v151
	ds_bpermute_b32 v174, v145, v152
	ds_bpermute_b32 v175, v145, v153
	s_waitcnt lgkmcnt(4)
	global_store_dwordx4 v144, v[168:171], s[10:11] nt
	s_add_u32 s54, s10, s12
	s_addc_u32 s55, s11, 0
	s_add_u32 s80, s28, s12
	s_addc_u32 s81, s29, 0
	v_fmamk_f32 v158, v246, 0x3a800000, v207
	v_rsq_f32_e32 v158, v158
	s_nop 0
	v_mul_f32_e32 v158, s100, v158
	v_pk_mul_f32 v[12:13], v[12:13], v[158:159] op_sel_hi:[1,0]
	v_pk_mul_f32 v[14:15], v[14:15], v[158:159] op_sel_hi:[1,0]
	v_pk_mul_f32 v[8:9], v[8:9], v[158:159] op_sel_hi:[1,0]
	v_pk_mul_f32 v[10:11], v[10:11], v[158:159] op_sel_hi:[1,0]
	v_cvt_pk_bf16_f32 v146, v12, v13
	v_cvt_pk_bf16_f32 v147, v14, v15
	v_cvt_pk_bf16_f32 v148, v8, v9
	v_cvt_pk_bf16_f32 v149, v10, v11
	ds_bpermute_b32 v168, v145, v146
	ds_bpermute_b32 v169, v145, v147
	ds_bpermute_b32 v170, v145, v148
	ds_bpermute_b32 v171, v145, v149
	s_waitcnt lgkmcnt(4)
	global_store_dwordx4 v144, v[172:175], s[28:29] nt
	v_pk_mul_f32 v[4:5], v[4:5], v[158:159] op_sel_hi:[1,0]
	v_pk_mul_f32 v[6:7], v[6:7], v[158:159] op_sel_hi:[1,0]
	v_pk_mul_f32 v[0:1], v[0:1], v[158:159] op_sel_hi:[1,0]
	v_pk_mul_f32 v[2:3], v[2:3], v[158:159] op_sel_hi:[1,0]
	v_cvt_pk_bf16_f32 v150, v4, v5
	v_cvt_pk_bf16_f32 v151, v6, v7
	v_cvt_pk_bf16_f32 v152, v0, v1
	v_cvt_pk_bf16_f32 v153, v2, v3
	ds_bpermute_b32 v172, v145, v150
	ds_bpermute_b32 v173, v145, v151
	ds_bpermute_b32 v174, v145, v152
	ds_bpermute_b32 v175, v145, v153
	s_waitcnt lgkmcnt(4)
	global_store_dwordx4 v144, v[168:171], s[54:55] nt
	s_waitcnt lgkmcnt(0)
	global_store_dwordx4 v144, v[172:175], s[80:81] nt
	s_branch .Lmy_b16_done
.Lmy_b16_norm:
	v_mov_b32_e32 v164, 0
	v_mov_b32_e32 v165, 0
	v_mov_b32_e32 v166, 0
	v_mov_b32_e32 v167, 0
	v_fmamk_f32 v158, v236, 0x3a800000, v207
	v_rsq_f32_e32 v158, v158
	s_nop 0
	v_mul_f32_e32 v158, s100, v158
	v_pk_mul_f32 v[126:127], v[126:127], v[158:159] op_sel_hi:[1,0]
	v_pk_mul_f32 v[128:129], v[128:129], v[158:159] op_sel_hi:[1,0]
	v_pk_mul_f32 v[122:123], v[122:123], v[158:159] op_sel_hi:[1,0]
	v_pk_mul_f32 v[124:125], v[124:125], v[158:159] op_sel_hi:[1,0]
	v_cvt_pk_bf16_f32 v146, v126, v127
	v_cvt_pk_bf16_f32 v147, v128, v129
	v_cvt_pk_bf16_f32 v148, v122, v123
	v_cvt_pk_bf16_f32 v149, v124, v125
	ds_bpermute_b32 v168, v145, v146
	ds_bpermute_b32 v169, v145, v147
	ds_bpermute_b32 v170, v145, v148
	ds_bpermute_b32 v171, v145, v149
	v_pk_mul_f32 v[126:127], v[126:127], v[126:127]
	v_pk_mul_f32 v[128:129], v[128:129], v[128:129]
	v_pk_mul_f32 v[122:123], v[122:123], v[122:123]
	v_pk_mul_f32 v[124:125], v[124:125], v[124:125]
	v_add_f32_e32 v160, v126, v127
	v_add_f32_e32 v161, v128, v129
	v_add_f32_e32 v162, v122, v123
	v_add_f32_e32 v163, v124, v125
	v_add_f32_e32 v160, v160, v161
	v_add_f32_e32 v160, v162, v160
	v_add_f32_e32 v160, v163, v160
	ds_swizzle_b32 v161, v160 offset:swizzle(SWAP,16)
	s_waitcnt lgkmcnt(0)
	global_store_dwordx4 v144, v[168:171], s[10:11] nt
	v_add_f32_e32 v160, v160, v161
	v_mov_b32_e32 v161, v160
	s_nop 1
	v_permlane32_swap_b32_e32 v160, v161
	v_add_f32_e32 v160, v160, v161
	v_max_f32_e32 v164, v164, v160
	v_pk_mul_f32 v[118:119], v[118:119], v[158:159] op_sel_hi:[1,0]
	v_pk_mul_f32 v[120:121], v[120:121], v[158:159] op_sel_hi:[1,0]
	v_pk_mul_f32 v[114:115], v[114:115], v[158:159] op_sel_hi:[1,0]
	v_pk_mul_f32 v[116:117], v[116:117], v[158:159] op_sel_hi:[1,0]
	v_cvt_pk_bf16_f32 v150, v118, v119
	v_cvt_pk_bf16_f32 v151, v120, v121
	v_cvt_pk_bf16_f32 v152, v114, v115
	v_cvt_pk_bf16_f32 v153, v116, v117
	ds_bpermute_b32 v172, v145, v150
	ds_bpermute_b32 v173, v145, v151
	ds_bpermute_b32 v174, v145, v152
	ds_bpermute_b32 v175, v145, v153
	v_pk_mul_f32 v[118:119], v[118:119], v[118:119]
	v_pk_mul_f32 v[120:121], v[120:121], v[120:121]
	v_pk_mul_f32 v[114:115], v[114:115], v[114:115]
	v_pk_mul_f32 v[116:117], v[116:117], v[116:117]
	v_add_f32_e32 v160, v118, v119
	v_add_f32_e32 v161, v120, v121
	v_add_f32_e32 v162, v114, v115
	v_add_f32_e32 v163, v116, v117
	v_add_f32_e32 v160, v160, v161
	v_add_f32_e32 v160, v162, v160
	v_add_f32_e32 v160, v163, v160
	ds_swizzle_b32 v161, v160 offset:swizzle(SWAP,16)
	s_waitcnt lgkmcnt(0)
	global_store_dwordx4 v144, v[172:175], s[28:29] nt
	v_add_f32_e32 v160, v160, v161
	v_mov_b32_e32 v161, v160
	s_nop 1
	v_permlane32_swap_b32_e32 v160, v161
	v_add_f32_e32 v160, v160, v161
	v_max_f32_e32 v165, v165, v160
	s_add_u32 s54, s10, s12
	s_addc_u32 s55, s11, 0
	s_add_u32 s80, s28, s12
	s_addc_u32 s81, s29, 0
	v_fmamk_f32 v158, v237, 0x3a800000, v207
	v_rsq_f32_e32 v158, v158
	s_nop 0
	v_mul_f32_e32 v158, s100, v158
	v_pk_mul_f32 v[110:111], v[110:111], v[158:159] op_sel_hi:[1,0]
	v_pk_mul_f32 v[112:113], v[112:113], v[158:159] op_sel_hi:[1,0]
	v_pk_mul_f32 v[106:107], v[106:107], v[158:159] op_sel_hi:[1,0]
	v_pk_mul_f32 v[108:109], v[108:109], v[158:159] op_sel_hi:[1,0]
	v_cvt_pk_bf16_f32 v146, v110, v111
	v_cvt_pk_bf16_f32 v147, v112, v113
	v_cvt_pk_bf16_f32 v148, v106, v107
	v_cvt_pk_bf16_f32 v149, v108, v109
	ds_bpermute_b32 v168, v145, v146
	ds_bpermute_b32 v169, v145, v147
	ds_bpermute_b32 v170, v145, v148
	ds_bpermute_b32 v171, v145, v149
	v_pk_mul_f32 v[110:111], v[110:111], v[110:111]
	v_pk_mul_f32 v[112:113], v[112:113], v[112:113]
	v_pk_mul_f32 v[106:107], v[106:107], v[106:107]
	v_pk_mul_f32 v[108:109], v[108:109], v[108:109]
	v_add_f32_e32 v160, v110, v111
	v_add_f32_e32 v161, v112, v113
	v_add_f32_e32 v162, v106, v107
	v_add_f32_e32 v163, v108, v109
	v_add_f32_e32 v160, v160, v161
	v_add_f32_e32 v160, v162, v160
	v_add_f32_e32 v160, v163, v160
	ds_swizzle_b32 v161, v160 offset:swizzle(SWAP,16)
	s_waitcnt lgkmcnt(0)
	global_store_dwordx4 v144, v[168:171], s[54:55] nt
	v_add_f32_e32 v160, v160, v161
	v_mov_b32_e32 v161, v160
	s_nop 1
	v_permlane32_swap_b32_e32 v160, v161
	v_add_f32_e32 v160, v160, v161
	v_max_f32_e32 v164, v164, v160
	v_pk_mul_f32 v[102:103], v[102:103], v[158:159] op_sel_hi:[1,0]
	v_pk_mul_f32 v[104:105], v[104:105], v[158:159] op_sel_hi:[1,0]
	v_pk_mul_f32 v[96:97], v[96:97], v[158:159] op_sel_hi:[1,0]
	v_pk_mul_f32 v[98:99], v[98:99], v[158:159] op_sel_hi:[1,0]
	v_cvt_pk_bf16_f32 v150, v102, v103
	v_cvt_pk_bf16_f32 v151, v104, v105
	v_cvt_pk_bf16_f32 v152, v96, v97
	v_cvt_pk_bf16_f32 v153, v98, v99
	ds_bpermute_b32 v172, v145, v150
	ds_bpermute_b32 v173, v145, v151
	ds_bpermute_b32 v174, v145, v152
	ds_bpermute_b32 v175, v145, v153
	v_pk_mul_f32 v[102:103], v[102:103], v[102:103]
	v_pk_mul_f32 v[104:105], v[104:105], v[104:105]
	v_pk_mul_f32 v[96:97], v[96:97], v[96:97]
	v_pk_mul_f32 v[98:99], v[98:99], v[98:99]
	v_add_f32_e32 v160, v102, v103
	v_add_f32_e32 v161, v104, v105
	v_add_f32_e32 v162, v96, v97
	v_add_f32_e32 v163, v98, v99
	v_add_f32_e32 v160, v160, v161
	v_add_f32_e32 v160, v162, v160
	v_add_f32_e32 v160, v163, v160
	ds_swizzle_b32 v161, v160 offset:swizzle(SWAP,16)
	s_waitcnt lgkmcnt(0)
	global_store_dwordx4 v144, v[172:175], s[80:81] nt
	v_add_f32_e32 v160, v160, v161
	v_mov_b32_e32 v161, v160
	s_nop 1
	v_permlane32_swap_b32_e32 v160, v161
	v_add_f32_e32 v160, v160, v161
	v_max_f32_e32 v165, v165, v160
	s_add_u32 s10, s54, s12
	s_addc_u32 s11, s55, 0
	s_add_u32 s28, s80, s12
	s_addc_u32 s29, s81, 0
	v_fmamk_f32 v158, v238, 0x3a800000, v207
	v_rsq_f32_e32 v158, v158
	s_nop 0
	v_mul_f32_e32 v158, s100, v158
	v_pk_mul_f32 v[92:93], v[92:93], v[158:159] op_sel_hi:[1,0]
	v_pk_mul_f32 v[94:95], v[94:95], v[158:159] op_sel_hi:[1,0]
	v_pk_mul_f32 v[88:89], v[88:89], v[158:159] op_sel_hi:[1,0]
	v_pk_mul_f32 v[90:91], v[90:91], v[158:159] op_sel_hi:[1,0]
	v_cvt_pk_bf16_f32 v146, v92, v93
	v_cvt_pk_bf16_f32 v147, v94, v95
	v_cvt_pk_bf16_f32 v148, v88, v89
	v_cvt_pk_bf16_f32 v149, v90, v91
	ds_bpermute_b32 v168, v145, v146
	ds_bpermute_b32 v169, v145, v147
	ds_bpermute_b32 v170, v145, v148
	ds_bpermute_b32 v171, v145, v149
	v_pk_mul_f32 v[92:93], v[92:93], v[92:93]
	v_pk_mul_f32 v[94:95], v[94:95], v[94:95]
	v_pk_mul_f32 v[88:89], v[88:89], v[88:89]
	v_pk_mul_f32 v[90:91], v[90:91], v[90:91]
	v_add_f32_e32 v160, v92, v93
	v_add_f32_e32 v161, v94, v95
	v_add_f32_e32 v162, v88, v89
	v_add_f32_e32 v163, v90, v91
	v_add_f32_e32 v160, v160, v161
	v_add_f32_e32 v160, v162, v160
	v_add_f32_e32 v160, v163, v160
	ds_swizzle_b32 v161, v160 offset:swizzle(SWAP,16)
	s_waitcnt lgkmcnt(0)
	global_store_dwordx4 v144, v[168:171], s[10:11] nt
	v_add_f32_e32 v160, v160, v161
	v_mov_b32_e32 v161, v160
	s_nop 1
	v_permlane32_swap_b32_e32 v160, v161
	v_add_f32_e32 v160, v160, v161
	v_max_f32_e32 v164, v164, v160
	v_pk_mul_f32 v[84:85], v[84:85], v[158:159] op_sel_hi:[1,0]
	v_pk_mul_f32 v[86:87], v[86:87], v[158:159] op_sel_hi:[1,0]
	v_pk_mul_f32 v[80:81], v[80:81], v[158:159] op_sel_hi:[1,0]
	v_pk_mul_f32 v[82:83], v[82:83], v[158:159] op_sel_hi:[1,0]
	v_cvt_pk_bf16_f32 v150, v84, v85
	v_cvt_pk_bf16_f32 v151, v86, v87
	v_cvt_pk_bf16_f32 v152, v80, v81
	v_cvt_pk_bf16_f32 v153, v82, v83
	ds_bpermute_b32 v172, v145, v150
	ds_bpermute_b32 v173, v145, v151
	ds_bpermute_b32 v174, v145, v152
	ds_bpermute_b32 v175, v145, v153
	v_pk_mul_f32 v[84:85], v[84:85], v[84:85]
	v_pk_mul_f32 v[86:87], v[86:87], v[86:87]
	v_pk_mul_f32 v[80:81], v[80:81], v[80:81]
	v_pk_mul_f32 v[82:83], v[82:83], v[82:83]
	v_add_f32_e32 v160, v84, v85
	v_add_f32_e32 v161, v86, v87
	v_add_f32_e32 v162, v80, v81
	v_add_f32_e32 v163, v82, v83
	v_add_f32_e32 v160, v160, v161
	v_add_f32_e32 v160, v162, v160
	v_add_f32_e32 v160, v163, v160
	ds_swizzle_b32 v161, v160 offset:swizzle(SWAP,16)
	s_waitcnt lgkmcnt(0)
	global_store_dwordx4 v144, v[172:175], s[28:29] nt
	v_add_f32_e32 v160, v160, v161
	v_mov_b32_e32 v161, v160
	s_nop 1
	v_permlane32_swap_b32_e32 v160, v161
	v_add_f32_e32 v160, v160, v161
	v_max_f32_e32 v165, v165, v160
	s_add_u32 s54, s10, s12
	s_addc_u32 s55, s11, 0
	s_add_u32 s80, s28, s12
	s_addc_u32 s81, s29, 0
	v_fmamk_f32 v158, v239, 0x3a800000, v207
	v_rsq_f32_e32 v158, v158
	s_nop 0
	v_mul_f32_e32 v158, s100, v158
	v_pk_mul_f32 v[76:77], v[76:77], v[158:159] op_sel_hi:[1,0]
	v_pk_mul_f32 v[78:79], v[78:79], v[158:159] op_sel_hi:[1,0]
	v_pk_mul_f32 v[72:73], v[72:73], v[158:159] op_sel_hi:[1,0]
	v_pk_mul_f32 v[74:75], v[74:75], v[158:159] op_sel_hi:[1,0]
	v_cvt_pk_bf16_f32 v146, v76, v77
	v_cvt_pk_bf16_f32 v147, v78, v79
	v_cvt_pk_bf16_f32 v148, v72, v73
	v_cvt_pk_bf16_f32 v149, v74, v75
	ds_bpermute_b32 v168, v145, v146
	ds_bpermute_b32 v169, v145, v147
	ds_bpermute_b32 v170, v145, v148
	ds_bpermute_b32 v171, v145, v149
	v_pk_mul_f32 v[76:77], v[76:77], v[76:77]
	v_pk_mul_f32 v[78:79], v[78:79], v[78:79]
	v_pk_mul_f32 v[72:73], v[72:73], v[72:73]
	v_pk_mul_f32 v[74:75], v[74:75], v[74:75]
	v_add_f32_e32 v160, v76, v77
	v_add_f32_e32 v161, v78, v79
	v_add_f32_e32 v162, v72, v73
	v_add_f32_e32 v163, v74, v75
	v_add_f32_e32 v160, v160, v161
	v_add_f32_e32 v160, v162, v160
	v_add_f32_e32 v160, v163, v160
	ds_swizzle_b32 v161, v160 offset:swizzle(SWAP,16)
	s_waitcnt lgkmcnt(0)
	global_store_dwordx4 v144, v[168:171], s[54:55] nt
	v_add_f32_e32 v160, v160, v161
	v_mov_b32_e32 v161, v160
	s_nop 1
	v_permlane32_swap_b32_e32 v160, v161
	v_add_f32_e32 v160, v160, v161
	v_max_f32_e32 v164, v164, v160
	v_pk_mul_f32 v[68:69], v[68:69], v[158:159] op_sel_hi:[1,0]
	v_pk_mul_f32 v[70:71], v[70:71], v[158:159] op_sel_hi:[1,0]
	v_pk_mul_f32 v[64:65], v[64:65], v[158:159] op_sel_hi:[1,0]
	v_pk_mul_f32 v[66:67], v[66:67], v[158:159] op_sel_hi:[1,0]
	v_cvt_pk_bf16_f32 v150, v68, v69
	v_cvt_pk_bf16_f32 v151, v70, v71
	v_cvt_pk_bf16_f32 v152, v64, v65
	v_cvt_pk_bf16_f32 v153, v66, v67
	ds_bpermute_b32 v172, v145, v150
	ds_bpermute_b32 v173, v145, v151
	ds_bpermute_b32 v174, v145, v152
	ds_bpermute_b32 v175, v145, v153
	v_pk_mul_f32 v[68:69], v[68:69], v[68:69]
	v_pk_mul_f32 v[70:71], v[70:71], v[70:71]
	v_pk_mul_f32 v[64:65], v[64:65], v[64:65]
	v_pk_mul_f32 v[66:67], v[66:67], v[66:67]
	v_add_f32_e32 v160, v68, v69
	v_add_f32_e32 v161, v70, v71
	v_add_f32_e32 v162, v64, v65
	v_add_f32_e32 v163, v66, v67
	v_add_f32_e32 v160, v160, v161
	v_add_f32_e32 v160, v162, v160
	v_add_f32_e32 v160, v163, v160
	ds_swizzle_b32 v161, v160 offset:swizzle(SWAP,16)
	s_waitcnt lgkmcnt(0)
	global_store_dwordx4 v144, v[172:175], s[80:81] nt
	v_add_f32_e32 v160, v160, v161
	v_mov_b32_e32 v161, v160
	s_nop 1
	v_permlane32_swap_b32_e32 v160, v161
	v_add_f32_e32 v160, v160, v161
	v_max_f32_e32 v165, v165, v160
	s_add_u32 s10, s54, s13
	s_addc_u32 s11, s55, 0
	s_add_u32 s28, s80, s13
	s_addc_u32 s29, s81, 0
	v_fmamk_f32 v158, v240, 0x3a800000, v207
	v_rsq_f32_e32 v158, v158
	s_nop 0
	v_mul_f32_e32 v158, s100, v158
	v_pk_mul_f32 v[60:61], v[60:61], v[158:159] op_sel_hi:[1,0]
	v_pk_mul_f32 v[62:63], v[62:63], v[158:159] op_sel_hi:[1,0]
	v_pk_mul_f32 v[56:57], v[56:57], v[158:159] op_sel_hi:[1,0]
	v_pk_mul_f32 v[58:59], v[58:59], v[158:159] op_sel_hi:[1,0]
	v_cvt_pk_bf16_f32 v146, v60, v61
	v_cvt_pk_bf16_f32 v147, v62, v63
	v_cvt_pk_bf16_f32 v148, v56, v57
	v_cvt_pk_bf16_f32 v149, v58, v59
	ds_bpermute_b32 v168, v145, v146
	ds_bpermute_b32 v169, v145, v147
	ds_bpermute_b32 v170, v145, v148
	ds_bpermute_b32 v171, v145, v149
	v_pk_mul_f32 v[60:61], v[60:61], v[60:61]
	v_pk_mul_f32 v[62:63], v[62:63], v[62:63]
	v_pk_mul_f32 v[56:57], v[56:57], v[56:57]
	v_pk_mul_f32 v[58:59], v[58:59], v[58:59]
	v_add_f32_e32 v160, v60, v61
	v_add_f32_e32 v161, v62, v63
	v_add_f32_e32 v162, v56, v57
	v_add_f32_e32 v163, v58, v59
	v_add_f32_e32 v160, v160, v161
	v_add_f32_e32 v160, v162, v160
	v_add_f32_e32 v160, v163, v160
	ds_swizzle_b32 v161, v160 offset:swizzle(SWAP,16)
	s_waitcnt lgkmcnt(0)
	global_store_dwordx4 v144, v[168:171], s[10:11] nt
	v_add_f32_e32 v160, v160, v161
	v_mov_b32_e32 v161, v160
	s_nop 1
	v_permlane32_swap_b32_e32 v160, v161
	v_add_f32_e32 v160, v160, v161
	v_max_f32_e32 v166, v166, v160
	v_pk_mul_f32 v[52:53], v[52:53], v[158:159] op_sel_hi:[1,0]
	v_pk_mul_f32 v[54:55], v[54:55], v[158:159] op_sel_hi:[1,0]
	v_pk_mul_f32 v[48:49], v[48:49], v[158:159] op_sel_hi:[1,0]
	v_pk_mul_f32 v[50:51], v[50:51], v[158:159] op_sel_hi:[1,0]
	v_cvt_pk_bf16_f32 v150, v52, v53
	v_cvt_pk_bf16_f32 v151, v54, v55
	v_cvt_pk_bf16_f32 v152, v48, v49
	v_cvt_pk_bf16_f32 v153, v50, v51
	ds_bpermute_b32 v172, v145, v150
	ds_bpermute_b32 v173, v145, v151
	ds_bpermute_b32 v174, v145, v152
	ds_bpermute_b32 v175, v145, v153
	v_pk_mul_f32 v[52:53], v[52:53], v[52:53]
	v_pk_mul_f32 v[54:55], v[54:55], v[54:55]
	v_pk_mul_f32 v[48:49], v[48:49], v[48:49]
	v_pk_mul_f32 v[50:51], v[50:51], v[50:51]
	v_add_f32_e32 v160, v52, v53
	v_add_f32_e32 v161, v54, v55
	v_add_f32_e32 v162, v48, v49
	v_add_f32_e32 v163, v50, v51
	v_add_f32_e32 v160, v160, v161
	v_add_f32_e32 v160, v162, v160
	v_add_f32_e32 v160, v163, v160
	ds_swizzle_b32 v161, v160 offset:swizzle(SWAP,16)
	s_waitcnt lgkmcnt(0)
	global_store_dwordx4 v144, v[172:175], s[28:29] nt
	v_add_f32_e32 v160, v160, v161
	v_mov_b32_e32 v161, v160
	s_nop 1
	v_permlane32_swap_b32_e32 v160, v161
	v_add_f32_e32 v160, v160, v161
	v_max_f32_e32 v167, v167, v160
	s_add_u32 s54, s10, s12
	s_addc_u32 s55, s11, 0
	s_add_u32 s80, s28, s12
	s_addc_u32 s81, s29, 0
	v_fmamk_f32 v158, v244, 0x3a800000, v207
	v_rsq_f32_e32 v158, v158
	s_nop 0
	v_mul_f32_e32 v158, s100, v158
	v_pk_mul_f32 v[44:45], v[44:45], v[158:159] op_sel_hi:[1,0]
	v_pk_mul_f32 v[46:47], v[46:47], v[158:159] op_sel_hi:[1,0]
	v_pk_mul_f32 v[40:41], v[40:41], v[158:159] op_sel_hi:[1,0]
	v_pk_mul_f32 v[42:43], v[42:43], v[158:159] op_sel_hi:[1,0]
	v_cvt_pk_bf16_f32 v146, v44, v45
	v_cvt_pk_bf16_f32 v147, v46, v47
	v_cvt_pk_bf16_f32 v148, v40, v41
	v_cvt_pk_bf16_f32 v149, v42, v43
	ds_bpermute_b32 v168, v145, v146
	ds_bpermute_b32 v169, v145, v147
	ds_bpermute_b32 v170, v145, v148
	ds_bpermute_b32 v171, v145, v149
	v_pk_mul_f32 v[44:45], v[44:45], v[44:45]
	v_pk_mul_f32 v[46:47], v[46:47], v[46:47]
	v_pk_mul_f32 v[40:41], v[40:41], v[40:41]
	v_pk_mul_f32 v[42:43], v[42:43], v[42:43]
	v_add_f32_e32 v160, v44, v45
	v_add_f32_e32 v161, v46, v47
	v_add_f32_e32 v162, v40, v41
	v_add_f32_e32 v163, v42, v43
	v_add_f32_e32 v160, v160, v161
	v_add_f32_e32 v160, v162, v160
	v_add_f32_e32 v160, v163, v160
	ds_swizzle_b32 v161, v160 offset:swizzle(SWAP,16)
	s_waitcnt lgkmcnt(0)
	global_store_dwordx4 v144, v[168:171], s[54:55] nt
	v_add_f32_e32 v160, v160, v161
	v_mov_b32_e32 v161, v160
	s_nop 1
	v_permlane32_swap_b32_e32 v160, v161
	v_add_f32_e32 v160, v160, v161
	v_max_f32_e32 v166, v166, v160
	v_pk_mul_f32 v[36:37], v[36:37], v[158:159] op_sel_hi:[1,0]
	v_pk_mul_f32 v[38:39], v[38:39], v[158:159] op_sel_hi:[1,0]
	v_pk_mul_f32 v[32:33], v[32:33], v[158:159] op_sel_hi:[1,0]
	v_pk_mul_f32 v[34:35], v[34:35], v[158:159] op_sel_hi:[1,0]
	v_cvt_pk_bf16_f32 v150, v36, v37
	v_cvt_pk_bf16_f32 v151, v38, v39
	v_cvt_pk_bf16_f32 v152, v32, v33
	v_cvt_pk_bf16_f32 v153, v34, v35
	ds_bpermute_b32 v172, v145, v150
	ds_bpermute_b32 v173, v145, v151
	ds_bpermute_b32 v174, v145, v152
	ds_bpermute_b32 v175, v145, v153
	v_pk_mul_f32 v[36:37], v[36:37], v[36:37]
	v_pk_mul_f32 v[38:39], v[38:39], v[38:39]
	v_pk_mul_f32 v[32:33], v[32:33], v[32:33]
	v_pk_mul_f32 v[34:35], v[34:35], v[34:35]
	v_add_f32_e32 v160, v36, v37
	v_add_f32_e32 v161, v38, v39
	v_add_f32_e32 v162, v32, v33
	v_add_f32_e32 v163, v34, v35
	v_add_f32_e32 v160, v160, v161
	v_add_f32_e32 v160, v162, v160
	v_add_f32_e32 v160, v163, v160
	ds_swizzle_b32 v161, v160 offset:swizzle(SWAP,16)
	s_waitcnt lgkmcnt(0)
	global_store_dwordx4 v144, v[172:175], s[80:81] nt
	v_add_f32_e32 v160, v160, v161
	v_mov_b32_e32 v161, v160
	s_nop 1
	v_permlane32_swap_b32_e32 v160, v161
	v_add_f32_e32 v160, v160, v161
	v_max_f32_e32 v167, v167, v160
	s_add_u32 s10, s54, s12
	s_addc_u32 s11, s55, 0
	s_add_u32 s28, s80, s12
	s_addc_u32 s29, s81, 0
	v_fmamk_f32 v158, v245, 0x3a800000, v207
	v_rsq_f32_e32 v158, v158
	s_nop 0
	v_mul_f32_e32 v158, s100, v158
	v_pk_mul_f32 v[28:29], v[28:29], v[158:159] op_sel_hi:[1,0]
	v_pk_mul_f32 v[30:31], v[30:31], v[158:159] op_sel_hi:[1,0]
	v_pk_mul_f32 v[24:25], v[24:25], v[158:159] op_sel_hi:[1,0]
	v_pk_mul_f32 v[26:27], v[26:27], v[158:159] op_sel_hi:[1,0]
	v_cvt_pk_bf16_f32 v146, v28, v29
	v_cvt_pk_bf16_f32 v147, v30, v31
	v_cvt_pk_bf16_f32 v148, v24, v25
	v_cvt_pk_bf16_f32 v149, v26, v27
	ds_bpermute_b32 v168, v145, v146
	ds_bpermute_b32 v169, v145, v147
	ds_bpermute_b32 v170, v145, v148
	ds_bpermute_b32 v171, v145, v149
	v_pk_mul_f32 v[28:29], v[28:29], v[28:29]
	v_pk_mul_f32 v[30:31], v[30:31], v[30:31]
	v_pk_mul_f32 v[24:25], v[24:25], v[24:25]
	v_pk_mul_f32 v[26:27], v[26:27], v[26:27]
	v_add_f32_e32 v160, v28, v29
	v_add_f32_e32 v161, v30, v31
	v_add_f32_e32 v162, v24, v25
	v_add_f32_e32 v163, v26, v27
	v_add_f32_e32 v160, v160, v161
	v_add_f32_e32 v160, v162, v160
	v_add_f32_e32 v160, v163, v160
	ds_swizzle_b32 v161, v160 offset:swizzle(SWAP,16)
	s_waitcnt lgkmcnt(0)
	global_store_dwordx4 v144, v[168:171], s[10:11] nt
	v_add_f32_e32 v160, v160, v161
	v_mov_b32_e32 v161, v160
	s_nop 1
	v_permlane32_swap_b32_e32 v160, v161
	v_add_f32_e32 v160, v160, v161
	v_max_f32_e32 v166, v166, v160
	v_pk_mul_f32 v[20:21], v[20:21], v[158:159] op_sel_hi:[1,0]
	v_pk_mul_f32 v[22:23], v[22:23], v[158:159] op_sel_hi:[1,0]
	v_pk_mul_f32 v[16:17], v[16:17], v[158:159] op_sel_hi:[1,0]
	v_pk_mul_f32 v[18:19], v[18:19], v[158:159] op_sel_hi:[1,0]
	v_cvt_pk_bf16_f32 v150, v20, v21
	v_cvt_pk_bf16_f32 v151, v22, v23
	v_cvt_pk_bf16_f32 v152, v16, v17
	v_cvt_pk_bf16_f32 v153, v18, v19
	ds_bpermute_b32 v172, v145, v150
	ds_bpermute_b32 v173, v145, v151
	ds_bpermute_b32 v174, v145, v152
	ds_bpermute_b32 v175, v145, v153
	v_pk_mul_f32 v[20:21], v[20:21], v[20:21]
	v_pk_mul_f32 v[22:23], v[22:23], v[22:23]
	v_pk_mul_f32 v[16:17], v[16:17], v[16:17]
	v_pk_mul_f32 v[18:19], v[18:19], v[18:19]
	v_add_f32_e32 v160, v20, v21
	v_add_f32_e32 v161, v22, v23
	v_add_f32_e32 v162, v16, v17
	v_add_f32_e32 v163, v18, v19
	v_add_f32_e32 v160, v160, v161
	v_add_f32_e32 v160, v162, v160
	v_add_f32_e32 v160, v163, v160
	ds_swizzle_b32 v161, v160 offset:swizzle(SWAP,16)
	s_waitcnt lgkmcnt(0)
	global_store_dwordx4 v144, v[172:175], s[28:29] nt
	v_add_f32_e32 v160, v160, v161
	v_mov_b32_e32 v161, v160
	s_nop 1
	v_permlane32_swap_b32_e32 v160, v161
	v_add_f32_e32 v160, v160, v161
	v_max_f32_e32 v167, v167, v160
	s_add_u32 s54, s10, s12
	s_addc_u32 s55, s11, 0
	s_add_u32 s80, s28, s12
	s_addc_u32 s81, s29, 0
	v_fmamk_f32 v158, v246, 0x3a800000, v207
	v_rsq_f32_e32 v158, v158
	s_nop 0
	v_mul_f32_e32 v158, s100, v158
	v_pk_mul_f32 v[12:13], v[12:13], v[158:159] op_sel_hi:[1,0]
	v_pk_mul_f32 v[14:15], v[14:15], v[158:159] op_sel_hi:[1,0]
	v_pk_mul_f32 v[8:9], v[8:9], v[158:159] op_sel_hi:[1,0]
	v_pk_mul_f32 v[10:11], v[10:11], v[158:159] op_sel_hi:[1,0]
	v_cvt_pk_bf16_f32 v146, v12, v13
	v_cvt_pk_bf16_f32 v147, v14, v15
	v_cvt_pk_bf16_f32 v148, v8, v9
	v_cvt_pk_bf16_f32 v149, v10, v11
	ds_bpermute_b32 v168, v145, v146
	ds_bpermute_b32 v169, v145, v147
	ds_bpermute_b32 v170, v145, v148
	ds_bpermute_b32 v171, v145, v149
	v_pk_mul_f32 v[12:13], v[12:13], v[12:13]
	v_pk_mul_f32 v[14:15], v[14:15], v[14:15]
	v_pk_mul_f32 v[8:9], v[8:9], v[8:9]
	v_pk_mul_f32 v[10:11], v[10:11], v[10:11]
	v_add_f32_e32 v160, v12, v13
	v_add_f32_e32 v161, v14, v15
	v_add_f32_e32 v162, v8, v9
	v_add_f32_e32 v163, v10, v11
	v_add_f32_e32 v160, v160, v161
	v_add_f32_e32 v160, v162, v160
	v_add_f32_e32 v160, v163, v160
	ds_swizzle_b32 v161, v160 offset:swizzle(SWAP,16)
	s_waitcnt lgkmcnt(0)
	global_store_dwordx4 v144, v[168:171], s[54:55] nt
	v_add_f32_e32 v160, v160, v161
	v_mov_b32_e32 v161, v160
	s_nop 1
	v_permlane32_swap_b32_e32 v160, v161
	v_add_f32_e32 v160, v160, v161
	v_max_f32_e32 v166, v166, v160
	v_pk_mul_f32 v[4:5], v[4:5], v[158:159] op_sel_hi:[1,0]
	v_pk_mul_f32 v[6:7], v[6:7], v[158:159] op_sel_hi:[1,0]
	v_pk_mul_f32 v[0:1], v[0:1], v[158:159] op_sel_hi:[1,0]
	v_pk_mul_f32 v[2:3], v[2:3], v[158:159] op_sel_hi:[1,0]
	v_cvt_pk_bf16_f32 v150, v4, v5
	v_cvt_pk_bf16_f32 v151, v6, v7
	v_cvt_pk_bf16_f32 v152, v0, v1
	v_cvt_pk_bf16_f32 v153, v2, v3
	ds_bpermute_b32 v172, v145, v150
	ds_bpermute_b32 v173, v145, v151
	ds_bpermute_b32 v174, v145, v152
	ds_bpermute_b32 v175, v145, v153
	v_pk_mul_f32 v[4:5], v[4:5], v[4:5]
	v_pk_mul_f32 v[6:7], v[6:7], v[6:7]
	v_pk_mul_f32 v[0:1], v[0:1], v[0:1]
	v_pk_mul_f32 v[2:3], v[2:3], v[2:3]
	v_add_f32_e32 v160, v4, v5
	v_add_f32_e32 v161, v6, v7
	v_add_f32_e32 v162, v0, v1
	v_add_f32_e32 v163, v2, v3
	v_add_f32_e32 v160, v160, v161
	v_add_f32_e32 v160, v162, v160
	v_add_f32_e32 v160, v163, v160
	ds_swizzle_b32 v161, v160 offset:swizzle(SWAP,16)
	s_waitcnt lgkmcnt(0)
	global_store_dwordx4 v144, v[172:175], s[80:81] nt
	v_add_f32_e32 v160, v160, v161
	v_mov_b32_e32 v161, v160
	s_nop 1
	v_permlane32_swap_b32_e32 v160, v161
	v_add_f32_e32 v160, v160, v161
	v_max_f32_e32 v167, v167, v160
	ds_swizzle_b32 v160, v164 offset:swizzle(SWAP,1)
	s_waitcnt lgkmcnt(0)
	v_max_f32_e32 v164, v164, v160
	ds_swizzle_b32 v160, v164 offset:swizzle(SWAP,2)
	s_waitcnt lgkmcnt(0)
	v_max_f32_e32 v164, v164, v160
	ds_swizzle_b32 v160, v164 offset:swizzle(SWAP,4)
	s_waitcnt lgkmcnt(0)
	v_max_f32_e32 v164, v164, v160
	ds_swizzle_b32 v160, v164 offset:swizzle(SWAP,8)
	s_waitcnt lgkmcnt(0)
	v_max_f32_e32 v164, v164, v160
	ds_swizzle_b32 v160, v165 offset:swizzle(SWAP,1)
	s_waitcnt lgkmcnt(0)
	v_max_f32_e32 v165, v165, v160
	ds_swizzle_b32 v160, v165 offset:swizzle(SWAP,2)
	s_waitcnt lgkmcnt(0)
	v_max_f32_e32 v165, v165, v160
	ds_swizzle_b32 v160, v165 offset:swizzle(SWAP,4)
	s_waitcnt lgkmcnt(0)
	v_max_f32_e32 v165, v165, v160
	ds_swizzle_b32 v160, v165 offset:swizzle(SWAP,8)
	s_waitcnt lgkmcnt(0)
	v_max_f32_e32 v165, v165, v160
	ds_swizzle_b32 v160, v166 offset:swizzle(SWAP,1)
	s_waitcnt lgkmcnt(0)
	v_max_f32_e32 v166, v166, v160
	ds_swizzle_b32 v160, v166 offset:swizzle(SWAP,2)
	s_waitcnt lgkmcnt(0)
	v_max_f32_e32 v166, v166, v160
	ds_swizzle_b32 v160, v166 offset:swizzle(SWAP,4)
	s_waitcnt lgkmcnt(0)
	v_max_f32_e32 v166, v166, v160
	ds_swizzle_b32 v160, v166 offset:swizzle(SWAP,8)
	s_waitcnt lgkmcnt(0)
	v_max_f32_e32 v166, v166, v160
	ds_swizzle_b32 v160, v167 offset:swizzle(SWAP,1)
	s_waitcnt lgkmcnt(0)
	v_max_f32_e32 v167, v167, v160
	ds_swizzle_b32 v160, v167 offset:swizzle(SWAP,2)
	s_waitcnt lgkmcnt(0)
	v_max_f32_e32 v167, v167, v160
	ds_swizzle_b32 v160, v167 offset:swizzle(SWAP,4)
	s_waitcnt lgkmcnt(0)
	v_max_f32_e32 v167, v167, v160
	ds_swizzle_b32 v160, v167 offset:swizzle(SWAP,8)
	s_waitcnt lgkmcnt(0)
	v_max_f32_e32 v167, v167, v160
	s_ashr_i32 s11, s40, 5
	s_lshl_b32 s14, s47, 3
	s_add_i32 s14, s14, s11
	s_lshl_b32 s14, s14, 10
	s_ashr_i32 s15, s33, 6
	s_add_i32 s15, s15, s94
	s_lshl_b32 s15, s15, 6
	s_add_i32 s14, s14, s15
	s_lshl_b32 s15, s40, 1
	s_and_b32 s15, s15, 62
	s_or_b32 s14, s14, s15
	s_lshl_b32 s14, s14, 3
	s_add_u32 s14, s95, s14
	s_addc_u32 s15, s98, 0
	s_and_saveexec_b64 s[12:13], s[6:7]
	s_cbranch_execz .Lmy_b16_noatom
	global_atomic_umax v101, v164, s[14:15]
	global_atomic_umax v101, v165, s[14:15] offset:1024
	global_atomic_umax v101, v166, s[14:15] offset:8
	global_atomic_umax v101, v167, s[14:15] offset:1032
